# serpentine row-panel order: P4 and P8 start with the panel group the previous phase wrote last (L2/MALL-hot A operand), on top of v27
# speedup vs baseline: 1.0050x; 1.0028x over previous
; __device__ __forceinline__ int xcd_remap(int L, int nwg) { const int q = nwg / NXCD, r = nwg % NXCD, xcd = L % NXCD, off = L / NXCD; return (xcd < r ? xcd * (q + 1) : r * (q + 1) + (xcd - r) * q) + off; }
;     __device__ bool next(int i, Unit& u) const {
;         const long L = (long)i * G + c; if (L >= nwg) return false;
;         const int wgid = xcd_remap((int)L, nwg);
;         const int nig = WGM * nN, gid = wgid / nig, fm = gid * WGM, gsz = (nM - fm) < WGM ? (nM - fm) : WGM;
;         int pm = fm + ((wgid % nig) % gsz); const int pn = (wgid % nig) / gsz;
;         if (perm) { const int x = pm >> 4, j = pm & 15; pm = (j < 8) ? 8 * x + j : 64 + 8 * x + (j - 8); } u.aoff = (size_t)pm * atile; u.boff = (size_t)pn * btile + (size_t)(pm >> 3) * bbatch; u.r0 = pm * BM; u.c0 = pn * BM; u.sel = 0; return true;
; template <class Epi, class Sched>
; __device__ __forceinline__ void gemm_phase(PG8_LAS unsigned char* lds, PG8_LAS unsigned char* xl, const Gemm g, const Sched& S, const Epi& E) {
;     ...
;     if (!S.next(0, cur)) return;
.LBB0_564:
	s_add_i32 s10, s16, s10
	s_ashr_i32 s11, s10, 31
	s_lshr_b32 s11, s11, 27
	s_add_i32 s11, s10, s11
	s_ashr_i32 s12, s11, 5
	s_and_b32 s11, s11, 0xffe0
	s_sub_i32 s10, s10, s11
	s_bfe_i32 s11, s10, 0x80000
	s_bfe_u32 s11, s11, 0x3000c
	s_add_i32 s11, s10, s11
	s_lshl_b32 s16, s12, 3
	s_xor_b32 s16, s16, 8
	s_bfe_i32 s12, s11, 0x80000
	s_and_b32 s11, s11, 0xf8
	s_sub_i32 s10, s10, s11
	s_sext_i32_i8 s10, s10
	s_sext_i32_i16 s12, s12
	s_add_i32 s20, s16, s10
	s_lshr_b32 s12, s12, 3
	s_ashr_i32 s22, s20, 3
	s_ashr_i32 s21, s20, 31
	s_bfe_i64 s[16:17], s[12:13], 0x100000
	s_ashr_i32 s23, s22, 31
	s_lshl_b64 s[10:11], s[20:21], 19
	s_lshl_b64 s[16:17], s[16:17], 19
	s_lshl_b64 s[22:23], s[22:23], 21
	s_add_u32 s16, s22, s16
	s_addc_u32 s17, s23, s17
	s_lshl_b32 s58, s20, 8
	s_lshl_b32 s12, s12, 8
	s_add_i32 s54, 0, 0x22100
	s_andn2_b64 vcc, exec, s[18:19]
	v_lshl_add_u32 v154, v220, 2, s54
	s_cbranch_vccnz .LBB0_642

; __device__ __forceinline__ int xcd_remap(int L, int nwg) { const int q = nwg / NXCD, r = nwg % NXCD, xcd = L % NXCD, off = L / NXCD; return (xcd < r ? xcd * (q + 1) : r * (q + 1) + (xcd - r) * q) + off; }
;     __device__ bool next(int i, Unit& u) const {
;         const long L = (long)i * G + c; if (L >= nwg) return false;
;         const int wgid = xcd_remap((int)L, nwg);
;         const int nig = WGM * nN, gid = wgid / nig, fm = gid * WGM, gsz = (nM - fm) < WGM ? (nM - fm) : WGM;
;         int pm = fm + ((wgid % nig) % gsz); const int pn = (wgid % nig) / gsz;
;         if (perm) { const int x = pm >> 4, j = pm & 15; pm = (j < 8) ? 8 * x + j : 64 + 8 * x + (j - 8); } u.aoff = (size_t)pm * atile; u.boff = (size_t)pn * btile + (size_t)(pm >> 3) * bbatch; u.r0 = pm * BM; u.c0 = pn * BM; u.sel = 0; return true;
.LBB0_575:
	s_ashr_i32 s13, s13, 3
	s_add_i32 s13, s31, s13
	s_ashr_i32 s28, s13, 31
	s_lshr_b32 s28, s28, 27
	s_add_i32 s28, s13, s28
	s_ashr_i32 s29, s28, 5
	s_lshl_b32 s29, s29, 3
	s_xor_b32 s29, s29, 8
	s_sub_i32 s30, 0x80, s29
	s_min_i32 s30, s30, 8
	s_abs_i32 s31, s30
	v_cvt_f32_u32_e32 v0, s31
	s_sub_i32 s34, 0, s31
	s_andn2_b32 s28, s28, 31
	s_sub_i32 s13, s13, s28
	v_rcp_iflag_f32_e32 v0, v0
	s_abs_i32 s28, s13
	s_xor_b32 s33, s13, s30
	s_ashr_i32 s33, s33, 31
	v_mul_f32_e32 v0, 0x4f7ffffe, v0
	v_cvt_u32_f32_e32 v0, v0
	s_nop 0
	v_readfirstlane_b32 s35, v0
	s_mul_i32 s34, s34, s35
	s_mul_hi_u32 s34, s35, s34
	s_add_i32 s35, s35, s34
	s_mul_hi_u32 s34, s28, s35
	s_mul_i32 s35, s34, s31
	s_sub_i32 s28, s28, s35
	s_add_i32 s36, s34, 1
	s_sub_i32 s35, s28, s31
	s_cmp_ge_u32 s28, s31
	s_cselect_b32 s34, s36, s34
	s_cselect_b32 s28, s35, s28
	s_add_i32 s35, s34, 1
	s_cmp_ge_u32 s28, s31
	s_cselect_b32 s28, s35, s34
	s_xor_b32 s28, s28, s33
	s_sub_i32 s34, s28, s33
	s_mul_i32 s28, s34, s30
	s_sub_i32 s13, s13, s28
	s_add_i32 s36, s29, s13
	s_ashr_i32 s46, s36, 3
	s_ashr_i32 s35, s34, 31
	s_ashr_i32 s37, s36, 31
	s_ashr_i32 s47, s46, 31
	s_lshl_b64 s[28:29], s[36:37], 19
	s_lshl_b64 s[30:31], s[34:35], 19
	s_lshl_b64 s[46:47], s[46:47], 21
	s_add_u32 s30, s46, s30
	s_addc_u32 s31, s47, s31
	s_lshl_b32 s78, s36, 8
	s_lshl_b32 s77, s34, 8

; #define PG8_BAR __builtin_amdgcn_s_barrier()
;     __device__ bool next(int i, Unit& u) const {
;         const long L = (long)i * G + c; if (L >= nwg) return false;
;         const int wgid = xcd_remap((int)L, nwg);
;         const int nig = WGM * nN, gid = wgid / nig, fm = gid * WGM, gsz = (nM - fm) < WGM ? (nM - fm) : WGM;
;         int pm = fm + ((wgid % nig) % gsz); const int pn = (wgid % nig) / gsz;
;         if (perm) { const int x = pm >> 4, j = pm & 15; pm = (j < 8) ? 8 * x + j : 64 + 8 * x + (j - 8); } u.aoff = (size_t)pm * atile; u.boff = (size_t)pn * btile + (size_t)(pm >> 3) * bbatch; u.r0 = pm * BM; u.c0 = pn * BM; u.sel = 0; return true;
; template <class Epi, class Sched>
; __device__ __forceinline__ void gemm_phase(PG8_LAS unsigned char* lds, PG8_LAS unsigned char* xl, const Gemm g, const Sched& S, const Epi& E) {
;     ...
;     const int tid = tid_, wid = __builtin_amdgcn_readfirstlane(tid >> 6), lane = tid & 63, wr = wid >> 2, wc = wid & 3, fr = lane & 15, fq = lane >> 4;
;     const int K = g.K, nt = K / BK;
;     unsigned voffA[2], voffB[2];
; #pragma unroll
;     for (int i = 0; i < 2; ++i) { int R, C; stage_rc(tid * 16 + i * 8192, R, C); const int Rb = (R & ~31) + perm32(R & 31);
;         voffA[i] = (unsigned)(R * g.lda + C) * 2u; voffB[i] = (unsigned)(Rb * g.ldb + C) * 2u; }
;     const size_t kstep = (size_t)(BK * 2);
;     const size_t hsA = (size_t)HALF * g.lda * 2, hsB = (size_t)HALF * g.ldb * 2;
;     const unsigned ldsw = (unsigned)wid * 1024u;
;     const int aoff = lds_byte(wr * 64 + fr, fq * 8), boff = lds_byte(wc * 32 + fr, fq * 8);
;     ...
;     Unit cur, nxt; int ui = 0;
;     if (!S.next(0, cur)) return;
;     Acc acc;
; #pragma unroll
;     for (int a = 0; a < 2; ++a)
; #pragma unroll
;         for (int b = 0; b < 2; ++b)
; #pragma unroll
;             for (int m = 0; m < 4; ++m)
; #pragma unroll
;                 for (int n = 0; n < 2; ++n) acc[a][b][m][n] = (f32x4){0.f, 0.f, 0.f, 0.f};
;     bf16x8 At[4][2], B0[2][2], B1[2][2];
;     const char* cA = (const char*)g.A + cur.aoff; const char* cB = (const char*)g.Bt + cur.boff;
;     PG8_STAGE(PG8_SB(0, 0), cB, voffB); PG8_STAGE(PG8_SB(0, 1), cB + hsB, voffB); PG8_STAGE(PG8_SA(0, 0), cA, voffA); PG8_STAGE(PG8_SA(0, 1), cA + hsA, voffA);
;     if (wr == 1) PG8_BAR;
.LBB0_817:
	v_lshlrev_b32_e32 v0, 4, v10
	v_add_u32_e32 v1, 0x2000, v0
	v_ashrrev_i32_e32 v2, 31, v1
	v_lshrrev_b32_e32 v2, 22, v2
	v_add_u32_e32 v2, v1, v2
	v_ashrrev_i32_e32 v8, 10, v2
	v_mul_i32_i24_e32 v2, 0x400, v8
	v_sub_u32_e32 v1, v1, v2
	v_lshrrev_b32_e32 v2, 4, v1
	v_bitop3_b32 v1, v2, v1, 32 bitop3:0x6c
	v_ashrrev_i32_e32 v2, 31, v1
	v_lshrrev_b32_e32 v2, 26, v2
	v_add_u32_e32 v2, v1, v2
	v_lshlrev_b32_e32 v3, 3, v8
	v_ashrrev_i32_e32 v9, 6, v2
	v_and_b32_e32 v3, -16, v3
	v_add_u32_e32 v3, v9, v3
	s_add_u32 s37, s2, 0x4000000
	v_and_b32_e32 v4, 3, v9
	s_mov_b32 s2, 0x1fffe0
	v_lshrrev_b32_e32 v5, 2, v3
	v_lshlrev_b32_e32 v6, 1, v3
	v_and_b32_e32 v2, 0xc0, v2
	v_and_or_b32 v4, v3, s2, v4
	v_and_b32_e32 v5, 4, v5
	v_and_b32_e32 v6, 24, v6
	v_sub_u32_e32 v1, v1, v2
	v_mov_b32_e32 v2, 1
	v_or3_b32 v4, v4, v5, v6
	v_lshlrev_b32_e32 v5, 5, v8
	v_ashrrev_i16_sdwa v1, v2, sext(v1) dst_sel:DWORD dst_unused:UNUSED_PAD src0_sel:DWORD src1_sel:BYTE_0
	v_and_b32_e32 v5, 32, v5
	v_bfe_i32 v11, v1, 0, 16
	v_add_lshl_u32 v1, v5, v11, 1
	v_lshl_add_u32 v128, v4, 11, v1
	v_lshl_add_u32 v130, v3, 11, v1
	v_bfe_i32 v1, v10, 27, 1
	v_lshrrev_b32_e32 v1, 22, v1
	v_add_u32_e32 v1, v0, v1
	v_and_b32_e32 v1, 0xfffffc00, v1
	v_sub_u32_e32 v0, v0, v1
	v_lshrrev_b32_e32 v1, 4, v0
	v_ashrrev_i32_e32 v3, 31, v10
	v_bitop3_b32 v0, v1, v0, 32 bitop3:0x6c
	v_lshrrev_b32_e32 v3, 26, v3
	v_ashrrev_i32_e32 v1, 31, v0
	v_add_u32_e32 v3, v10, v3
	v_lshrrev_b32_e32 v1, 26, v1
	v_ashrrev_i32_e32 v13, 6, v3
	s_addc_u32 s42, s3, 0
	v_add_u32_e32 v1, v0, v1
	v_lshlrev_b32_e32 v3, 3, v13
	s_add_u32 s43, s8, 0xf00000
	v_ashrrev_i32_e32 v12, 6, v1
	v_and_b32_e32 v3, -16, v3
	s_addc_u32 s50, s9, 0
	v_add_u32_e32 v3, v12, v3
	v_and_b32_e32 v4, 3, v12
	s_ashr_i32 s52, s36, 31
	v_and_or_b32 v4, v3, s2, v4
	s_lshr_b32 s2, s52, 29
	s_add_i32 s2, s36, s2
	s_ashr_i32 s16, s18, 6
	s_ashr_i32 s3, s2, 3
	s_and_b32 s2, s2, -8
	s_ashr_i32 s19, s18, 8
	s_lshl_b32 s51, s16, 10
	s_sub_i32 s2, s36, s2
	s_cmp_lt_i32 s2, 0
	s_movk_i32 s53, 0x161
	s_cselect_b32 s8, s53, 0x160
	s_mul_i32 s2, s2, s8
	s_add_i32 s2, s2, s3
	s_mul_hi_i32 s3, s2, 0x2e8ba2e9
	s_lshr_b32 s8, s3, 31
	s_ashr_i32 s3, s3, 5
	s_add_i32 s3, s3, s8
	s_lshl_b32 s9, s3, 3
	s_xor_b32 s9, s9, 8
	s_mulk_i32 s3, 0xb0
	s_sub_i32 s2, s2, s3
	s_bfe_u32 s3, s2, 0x3001c
	s_add_i32 s3, s2, s3
	s_sext_i32_i16 s8, s3
	s_and_b32 s3, s3, 0xfff8
	s_sub_i32 s2, s2, s3
	s_sext_i32_i16 s2, s2
	v_lshrrev_b32_e32 v5, 2, v3
	v_lshlrev_b32_e32 v6, 1, v3
	v_and_b32_e32 v1, 0xc0, v1
	s_lshr_b32 s8, s8, 3
	s_add_i32 s14, s9, s2
	v_and_b32_e32 v5, 4, v5
	v_and_b32_e32 v6, 24, v6
	v_sub_u32_e32 v0, v0, v1
	s_bfe_i64 s[2:3], s[8:9], 0x100000
	s_ashr_i32 s15, s14, 31
	v_or3_b32 v4, v4, v5, v6
	v_lshlrev_b32_e32 v5, 5, v13
	v_ashrrev_i16_sdwa v0, v2, sext(v0) dst_sel:DWORD dst_unused:UNUSED_PAD src0_sel:DWORD src1_sel:BYTE_0
	s_lshl_b64 s[2:3], s[2:3], 19
	s_lshl_b64 s[10:11], s[14:15], 19
	v_and_b32_e32 v5, 32, v5
	v_bfe_i32 v14, v0, 0, 16
	s_add_u32 s2, s43, s2
	v_add_lshl_u32 v0, v5, v14, 1
	s_addc_u32 s3, s50, s3
	s_add_i32 s55, s51, 0
	v_lshl_add_u32 v132, v4, 11, v0
	s_add_i32 m0, s55, 0x10000
	v_lshl_add_u32 v134, v3, 11, v0
	global_load_lds_dwordx4 v132, s[2:3]
	s_add_i32 m0, s55, 0x12000
	s_add_u32 s20, s2, 0x40000
	global_load_lds_dwordx4 v128, s[2:3]
	s_addc_u32 s21, s3, 0
	s_add_i32 m0, s55, 0x14000
	v_mov_b32_e32 v137, 0
	global_load_lds_dwordx4 v132, s[20:21]
	s_add_i32 m0, s55, 0x16000
	s_add_u32 s30, s37, s10
	s_addc_u32 s31, s42, s11
	s_add_i32 s56, s55, 0x2000
	global_load_lds_dwordx4 v128, s[20:21]
	s_mov_b32 m0, s55
	s_add_u32 s10, s30, 0x40000
	global_load_lds_dwordx4 v134, s[30:31]
	s_mov_b32 m0, s56
	s_addc_u32 s11, s31, 0
	s_add_i32 s57, s55, 0x4000
	global_load_lds_dwordx4 v130, s[30:31]
	s_mov_b32 m0, s57
	s_add_i32 s58, s55, 0x6000
	global_load_lds_dwordx4 v134, s[10:11]
	s_mov_b32 m0, s58
	v_mov_b32_e32 v133, v137
	global_load_lds_dwordx4 v130, s[10:11]
	v_mov_b32_e32 v129, v137
	v_mov_b32_e32 v135, v137
	v_mov_b32_e32 v131, v137
	s_cmp_eq_u32 s19, 1
	s_mov_b32 s9, 0
	v_lshl_add_u64 v[6:7], s[2:3], 0, v[132:133]
	v_lshl_add_u64 v[4:5], s[2:3], 0, v[128:129]
	v_lshl_add_u64 v[0:1], s[30:31], 0, v[134:135]
	s_cselect_b64 s[10:11], -1, 0
	s_cmp_lg_u32 s19, 1
	v_lshl_add_u64 v[2:3], s[30:31], 0, v[130:131]
	s_cbranch_scc1 .LBB0_819
	s_barrier

; __device__ __forceinline__ int xcd_remap(int L, int nwg) { const int q = nwg / NXCD, r = nwg % NXCD, xcd = L % NXCD, off = L / NXCD; return (xcd < r ? xcd * (q + 1) : r * (q + 1) + (xcd - r) * q) + off; }
;     __device__ bool next(int i, Unit& u) const {
;         const long L = (long)i * G + c; if (L >= nwg) return false;
;         const int wgid = xcd_remap((int)L, nwg);
;         const int nig = WGM * nN, gid = wgid / nig, fm = gid * WGM, gsz = (nM - fm) < WGM ? (nM - fm) : WGM;
;         int pm = fm + ((wgid % nig) % gsz); const int pn = (wgid % nig) / gsz;
;         if (perm) { const int x = pm >> 4, j = pm & 15; pm = (j < 8) ? 8 * x + j : 64 + 8 * x + (j - 8); } u.aoff = (size_t)pm * atile; u.boff = (size_t)pn * btile + (size_t)(pm >> 3) * bbatch; u.r0 = pm * BM; u.c0 = pn * BM; u.sel = 0; return true;
; template <class Epi, class Sched>
; __device__ __forceinline__ void gemm_phase(PG8_LAS unsigned char* lds, PG8_LAS unsigned char* xl, const Gemm g, const Sched& S, const Epi& E) {
;     ...
;         const bool has_next = S.next(ui + 1, nxt);
;         const char* nA = has_next ? (const char*)g.A + nxt.aoff : cA; const char* nB = has_next ? (const char*)g.Bt + nxt.boff : cB;
.LBB0_822:
	s_add_i32 s65, s65, 1
	s_mul_i32 s6, s65, s71
	s_mul_hi_u32 s7, s65, s40
	s_add_i32 s7, s7, s6
	s_mul_i32 s6, s65, s40
	s_add_u32 s26, s6, s36
	s_addc_u32 s27, s7, s52
	v_cmp_gt_i64_e32 vcc, s[26:27], v[144:145]
	v_cmp_lt_i64_e64 s[6:7], s[26:27], v[142:143]
	s_cbranch_vccnz .LBB0_824
	s_ashr_i32 s20, s26, 31
	s_lshr_b32 s20, s20, 29
	s_add_i32 s20, s26, s20
	s_ashr_i32 s21, s20, 3
	s_and_b32 s20, s20, -8
	s_sub_i32 s20, s26, s20
	s_cmp_lt_i32 s20, 0
	s_cselect_b32 s22, s53, 0x160
	s_mul_i32 s20, s20, s22
	s_add_i32 s20, s20, s21
	s_mul_hi_i32 s21, s20, 0x2e8ba2e9
	s_lshr_b32 s22, s21, 31
	s_ashr_i32 s21, s21, 5
	s_add_i32 s21, s21, s22
	s_lshl_b32 s22, s21, 3
	s_xor_b32 s22, s22, 8
	s_sub_i32 s23, 0x80, s22
	s_min_i32 s23, s23, 8
	s_abs_i32 s26, s23
	v_cvt_f32_u32_e32 v0, s26
	s_sub_i32 s28, 0, s26
	s_mulk_i32 s21, 0xb0
	s_sub_i32 s20, s20, s21
	v_rcp_iflag_f32_e32 v0, v0
	s_abs_i32 s21, s20
	s_xor_b32 s27, s20, s23
	s_ashr_i32 s27, s27, 31
	v_mul_f32_e32 v0, 0x4f7ffffe, v0
	v_cvt_u32_f32_e32 v0, v0
	s_nop 0
	v_readfirstlane_b32 s29, v0
	s_mul_i32 s28, s28, s29
	s_mul_hi_u32 s28, s29, s28
	s_add_i32 s29, s29, s28
	s_mul_hi_u32 s28, s21, s29
	s_mul_i32 s29, s28, s26
	s_sub_i32 s21, s21, s29
	s_add_i32 s34, s28, 1
	s_sub_i32 s29, s21, s26
	s_cmp_ge_u32 s21, s26
	s_cselect_b32 s28, s34, s28
	s_cselect_b32 s21, s29, s21
	s_add_i32 s29, s28, 1
	s_cmp_ge_u32 s21, s26
	s_cselect_b32 s21, s29, s28
	s_xor_b32 s21, s21, s27
	s_sub_i32 s26, s21, s27
	s_mul_i32 s21, s26, s23
	s_sub_i32 s20, s20, s21
	s_add_i32 s28, s22, s20
	s_ashr_i32 s29, s28, 31
	s_ashr_i32 s27, s26, 31
	s_lshl_b64 s[20:21], s[28:29], 19
	s_lshl_b64 s[22:23], s[26:27], 19
	s_lshl_b32 s67, s28, 8
	s_lshl_b32 s66, s26, 8
